# c1 plus one early L2 write-back per XCD by the fourth-to-last arriver at every grid barrier
# speedup vs baseline: 1.0016x; 1.0016x over previous
; __device__ __forceinline__ unsigned xb_ld(unsigned* p)              { return __hip_atomic_load(p, __ATOMIC_RELAXED, __HIP_MEMORY_SCOPE_AGENT); }
; __device__ __forceinline__ unsigned xb_add(unsigned* p, unsigned v) { return __hip_atomic_fetch_add(p, v, __ATOMIC_RELAXED, __HIP_MEMORY_SCOPE_AGENT); }
; #define XB_SPIN(cond, bar) do { unsigned _sp = 0; while (cond) { __builtin_amdgcn_s_sleep(1); \
;     if ((++_sp & 255u) == 0u) { if (xb_ld(&(bar)[XB_TMO])) break; if (_sp > XB_SPIN_CAP) { atomicAdd(&(bar)[XB_TMO], 1u); break; } } } } while (0)
; __device__ __forceinline__ void xcd_barrier(const XcdBarrier& b) {
;     ...
;         const unsigned old = xb_add(&bar[XB_XSUB(b.x)], 1u);
;         const unsigned gen = old / nloc;
;         if (old + 1u == (gen + 1u) * nloc) {
;             __builtin_amdgcn_fence(__ATOMIC_RELEASE, "agent");
;             asm volatile("s_waitcnt vmcnt(0)" ::: "memory");
;             const unsigned og = xb_add(&bar[XB_TOP], 1u);
;             const unsigned tg = og / nx;
;             if (og + 1u == (tg + 1u) * nx) xb_add(&bar[XB_TOPGEN], 1u);
;             else XB_SPIN(xb_ld(&bar[XB_TOPGEN]) == tg, bar);
;             __builtin_amdgcn_fence(__ATOMIC_ACQUIRE, "agent");
;             xb_add(&bar[XB_XGEN(b.x)], 1u);
;             asm volatile("s_waitcnt vmcnt(0)" ::: "memory");
;         } else {
;             XB_SPIN(xb_ld(&bar[XB_XGEN(b.x)]) == gen, bar);
;             __builtin_amdgcn_fence(__ATOMIC_ACQUIRE, "agent");
;             asm volatile("s_waitcnt vmcnt(0)" ::: "memory");
;         }
.LBB0_189:
	v_readlane_b32 s0, v252, 24
	v_readlane_b32 s1, v252, 25
	v_mov_b32_e32 v1, 1
	v_sub_u32_e32 v5, 0, v3
	s_nop 2
	global_atomic_add v4, v131, v1, s[0:1] sc0
	v_cvt_f32_u32_e32 v1, v3
	v_rcp_iflag_f32_e32 v1, v1
	s_nop 0
	v_mul_f32_e32 v1, 0x4f7ffffe, v1
	v_cvt_u32_f32_e32 v1, v1
	v_mul_lo_u32 v5, v5, v1
	v_mul_hi_u32 v5, v1, v5
	v_add_u32_e32 v1, v1, v5
	s_waitcnt vmcnt(0)
	v_mul_hi_u32 v1, v4, v1
	v_mul_lo_u32 v5, v1, v3
	v_sub_u32_e32 v5, v4, v5
	v_add_u32_e32 v6, 1, v1
	v_cmp_ge_u32_e32 vcc, v5, v3
	v_add_u32_e32 v4, 1, v4
	s_nop 0
	v_cndmask_b32_e32 v1, v1, v6, vcc
	v_sub_u32_e32 v6, v5, v3
	v_cndmask_b32_e32 v5, v5, v6, vcc
	v_add_u32_e32 v6, 1, v1
	v_cmp_ge_u32_e32 vcc, v5, v3
	s_nop 1
	v_cndmask_b32_e32 v1, v1, v6, vcc
	v_mul_lo_u32 v5, v3, v1
	v_add_u32_e32 v3, v5, v3
	v_cmp_ne_u32_e32 vcc, v4, v3
	s_and_saveexec_b64 s[0:1], vcc
	s_xor_b64 s[18:19], exec, s[0:1]
	s_cbranch_execz .LBB0_203
	v_add_u32_e32 v6, 3, v4
	v_cmp_eq_u32_e32 vcc, v6, v3
	s_cbranch_vccz .Lfa_1
	buffer_wbl2 sc1
.Lfa_1:
	v_readlane_b32 s0, v252, 26
	v_readlane_b32 s1, v252, 27
	s_waitcnt lgkmcnt(0)
	s_nop 3
	global_load_dword v2, v131, s[0:1] sc1
	s_waitcnt vmcnt(0)
	v_cmp_eq_u32_e32 vcc, v2, v1
	s_and_saveexec_b64 s[20:21], vcc
	s_cbranch_execz .LBB0_202
	s_mov_b32 s0, 1
	s_mov_b64 s[22:23], 0
	s_branch .LBB0_193
